# no store drain before the item barrier of the memory cross-attention items (P2, P12)
# speedup vs baseline: 1.0019x; 1.0019x over previous
.LBB0_312:
	s_ashr_i32 s34, s20, 6
	s_ashr_i32 s35, s34, 31
	s_lshl_b64 s[0:1], s[34:35], 12
	s_and_b32 s6, s14, 0xf00
	s_add_u32 s6, s6, s12
	s_addc_u32 s7, 0, s13
	s_add_u32 s0, s6, s0
	s_addc_u32 s1, s7, s1
	s_mulk_i32 s1, 0x1c00
	s_mul_hi_u32 s6, s0, 0x1c00
	s_add_i32 s6, s6, s1
	s_mulk_i32 s0, 0x1c00
	s_add_u32 s0, s60, s0
	s_addc_u32 s1, s61, s6
	s_and_b32 s6, s14, 0xc0
	s_lshl_b32 s8, s6, 1
	s_add_u32 s0, s0, s8
	s_addc_u32 s1, s1, 0
	s_add_u32 s6, s0, 0x1800
	s_addc_u32 s7, s1, 0
	s_add_u32 s0, s24, s8
	s_addc_u32 s1, s33, 0
	s_add_u32 s8, s10, s8
	s_addc_u32 s9, s11, 0
	s_lshl_b64 s[34:35], s[34:35], 18
	v_lshl_add_u64 v[64:65], s[34:35], 0, v[108:109]
	v_or_b32_e32 v0, v64, v100
	v_mov_b32_e32 v1, v65
	v_lshlrev_b64 v[0:1], 1, v[0:1]
	v_lshl_add_u64 v[2:3], s[0:1], 0, v[0:1]
	s_waitcnt lgkmcnt(0)
	s_barrier
	v_lshl_add_u64 v[0:1], s[8:9], 0, v[0:1]
	global_load_dwordx4 v[24:27], v[2:3], off
	global_load_dwordx4 v[28:31], v[0:1], off
	v_lshl_add_u64 v[0:1], s[6:7], 0, v[110:111]
	v_lshl_add_u64 v[0:1], v[0:1], 0, v[114:115]
	global_load_dwordx4 v[12:15], v[0:1], off
	v_add_co_u32_e32 v2, vcc, s16, v0
	v_lshl_add_u64 v[16:17], v[64:65], 0, v[102:103]
	s_nop 0
	v_addc_co_u32_e32 v3, vcc, 0, v1, vcc
	global_load_dwordx4 v[8:11], v[2:3], off
	global_load_dwordx4 v[4:7], v[0:1], off offset:64
	v_lshl_add_u64 v[0:1], v[0:1], 0, s[4:5]
	global_load_dwordx4 v[0:3], v[0:1], off offset:64
	v_lshlrev_b64 v[16:17], 1, v[16:17]
	v_lshl_add_u64 v[18:19], s[0:1], 0, v[16:17]
	v_lshl_add_u64 v[20:21], s[8:9], 0, v[16:17]
	global_load_dwordx4 v[16:19], v[18:19], off
	s_nop 0
	global_load_dwordx4 v[20:23], v[20:21], off
	s_waitcnt vmcnt(7)
	ds_write_b128 v101, v[24:27]
	s_waitcnt vmcnt(6)
	ds_write_b128 v101, v[28:31] offset:18432
	s_waitcnt lgkmcnt(0)
	s_barrier
	ds_read_b128 v[24:27], v118
	ds_read_b128 v[28:31], v118 offset:64
	ds_read_b128 v[36:39], v118 offset:2304
	ds_read_b128 v[40:43], v118 offset:2368
	ds_read_b128 v[48:51], v118 offset:4608
	ds_read_b128 v[52:55], v118 offset:4672
	ds_read_b128 v[60:63], v118 offset:6912
	ds_read_b128 v[66:69], v118 offset:6976
	s_waitcnt vmcnt(5) lgkmcnt(7)
	v_mfma_f32_16x16x32_bf16 v[32:35], v[24:27], v[12:15], 0
	s_waitcnt lgkmcnt(5)
	v_mfma_f32_16x16x32_bf16 v[44:47], v[36:39], v[12:15], 0
	s_waitcnt vmcnt(4)
	v_mfma_f32_16x16x32_bf16 v[24:27], v[24:27], v[8:11], 0
	v_mfma_f32_16x16x32_bf16 v[36:39], v[36:39], v[8:11], 0
	s_waitcnt lgkmcnt(3)
	v_mfma_f32_16x16x32_bf16 v[56:59], v[48:51], v[12:15], 0
	v_mfma_f32_16x16x32_bf16 v[48:51], v[48:51], v[8:11], 0
	s_waitcnt lgkmcnt(1)
	v_mfma_f32_16x16x32_bf16 v[70:73], v[60:63], v[12:15], 0
	s_waitcnt vmcnt(3)
	v_mfma_f32_16x16x32_bf16 v[32:35], v[28:31], v[4:7], v[32:35]
	v_mfma_f32_16x16x32_bf16 v[44:47], v[40:43], v[4:7], v[44:47]
	s_waitcnt vmcnt(2)
	v_mfma_f32_16x16x32_bf16 v[74:77], v[28:31], v[0:3], v[24:27]
	v_mfma_f32_16x16x32_bf16 v[36:39], v[40:43], v[0:3], v[36:39]
	v_mfma_f32_16x16x32_bf16 v[40:43], v[52:55], v[4:7], v[56:59]
	v_mfma_f32_16x16x32_bf16 v[28:31], v[52:55], v[0:3], v[48:51]
	s_nop 1
	v_max_f32_e32 v52, v35, v35
	v_max_f32_e32 v53, v34, v34
	v_max_f32_e32 v54, v47, v47
	s_waitcnt lgkmcnt(0)
	v_mfma_f32_16x16x32_bf16 v[48:51], v[66:69], v[4:7], v[70:73]
	v_max_f32_e32 v55, v46, v46
	v_max_f32_e32 v56, v43, v43
	v_max_f32_e32 v57, v42, v42
	v_max_f32_e32 v52, v53, v52
	v_max_f32_e32 v53, v55, v54
	s_nop 2
	v_max_f32_e32 v58, v51, v51
	v_max_f32_e32 v59, v50, v50
	v_max_f32_e32 v54, v57, v56
	v_max_f32_e32 v55, v59, v58
	v_max3_f32 v52, v32, v33, v52
	v_max3_f32 v53, v44, v45, v53
	v_max3_f32 v54, v40, v41, v54
	v_max3_f32 v55, v48, v49, v55
	v_max3_f32 v52, v52, s17, v53
	v_max3_f32 v52, v52, v54, v55
	v_mov_b32_e32 v53, v52
	s_nop 1
	v_permlane16_swap_b32_e32 v52, v53
	v_max_f32_e32 v53, v53, v53
	v_max_f32_e32 v52, v52, v52
	v_max_f32_e32 v52, v52, v53
	v_mov_b32_e32 v53, v52
	s_nop 1
	v_permlane32_swap_b32_e32 v52, v53
	v_max_f32_e32 v53, v53, v53
	v_max_f32_e32 v52, v52, v52
	v_max_f32_e32 v52, v52, v53
	v_fma_f32 v52, v52, s18, 0
	v_add_f32_e32 v53, 0x7149f2ca, v52
	v_cmp_ge_f32_e32 vcc, s19, v53
	s_cmp_eq_u64 vcc, exec
	v_max_f32_e32 v52, 0xf149f2ca, v52
	s_cselect_b64 vcc, -1, 0
	v_mfma_f32_16x16x32_bf16 v[60:63], v[60:63], v[8:11], 0
	v_cndmask_b32_e32 v113, v52, v120, vcc
	v_sub_f32_e32 v53, 0, v113
	v_fmamk_f32 v40, v40, 0x3e38aa3b, v53
	v_fmamk_f32 v41, v41, 0x3e38aa3b, v53
	v_fmamk_f32 v42, v42, 0x3e38aa3b, v53
	v_exp_f32_e32 v153, v40
	v_exp_f32_e32 v154, v41
	v_max_f32_e32 v40, v77, v77
	v_max_f32_e32 v41, v76, v76
	v_mfma_f32_16x16x32_bf16 v[24:27], v[66:69], v[0:3], v[60:63]
	v_exp_f32_e32 v155, v42
	v_max_f32_e32 v40, v41, v40
	v_max_f32_e32 v41, v39, v39
	v_max_f32_e32 v42, v38, v38
	v_max_f32_e32 v41, v42, v41
	v_max3_f32 v40, v74, v75, v40
	v_max3_f32 v41, v36, v37, v41
	v_fmamk_f32 v32, v32, 0x3e38aa3b, v53
	v_max3_f32 v40, v40, s17, v41
	v_max_f32_e32 v41, v31, v31
	v_max_f32_e32 v42, v30, v30
	v_exp_f32_e32 v122, v32
	v_fmamk_f32 v32, v43, 0x3e38aa3b, v53
	v_max_f32_e32 v41, v42, v41
	v_max_f32_e32 v42, v27, v27
	v_max_f32_e32 v43, v26, v26
	v_max_f32_e32 v42, v43, v42
	v_max3_f32 v41, v28, v29, v41
	v_max3_f32 v42, v24, v25, v42
	v_max3_f32 v40, v40, v41, v42
	v_mov_b32_e32 v41, v40
	s_nop 1
	v_permlane16_swap_b32_e32 v40, v41
	v_max_f32_e32 v41, v41, v41
	v_max_f32_e32 v40, v40, v40
	v_fmamk_f32 v33, v33, 0x3e38aa3b, v53
	v_max_f32_e32 v40, v40, v41
	v_exp_f32_e32 v146, v33
	v_sub_f32_e32 v33, 0xf149f2ca, v52
	v_mov_b32_e32 v41, v40
	v_exp_f32_e32 v33, v33
	s_nop 0
	v_permlane32_swap_b32_e32 v40, v41
	v_exp_f32_e32 v156, v32
	v_fmamk_f32 v32, v48, 0x3e38aa3b, v53
	v_max_f32_e32 v41, v41, v41
	v_max_f32_e32 v40, v40, v40
	v_exp_f32_e32 v157, v32
	v_fmamk_f32 v32, v49, 0x3e38aa3b, v53
	v_max_f32_e32 v40, v40, v41
	v_exp_f32_e32 v158, v32
	v_fmamk_f32 v32, v50, 0x3e38aa3b, v53
	v_fma_f32 v40, v40, s18, 0
	v_exp_f32_e32 v159, v32
	v_mul_f32_e32 v32, 0, v33
	v_add_f32_e32 v41, 0x7149f2ca, v40
	v_cndmask_b32_e64 v68, v32, 0, vcc
	v_cmp_ge_f32_e32 vcc, s19, v41
	s_cmp_eq_u64 vcc, exec
	v_max_f32_e32 v40, 0xf149f2ca, v40
	s_cselect_b64 vcc, -1, 0
	v_cndmask_b32_e32 v117, v40, v120, vcc
	v_sub_f32_e32 v60, 0, v117
	v_fmamk_f32 v36, v36, 0x3e38aa3b, v60
	v_exp_f32_e32 v126, v36
	v_fmamk_f32 v36, v37, 0x3e38aa3b, v60
	v_exp_f32_e32 v127, v36
	v_fmamk_f32 v36, v38, 0x3e38aa3b, v60
	v_exp_f32_e32 v128, v36
	v_sub_f32_e32 v36, 0xf149f2ca, v40
	v_fmamk_f32 v41, v74, 0x3e38aa3b, v60
	v_exp_f32_e32 v36, v36
	v_exp_f32_e32 v121, v41
	v_fmamk_f32 v41, v75, 0x3e38aa3b, v60
	v_exp_f32_e32 v123, v41
	v_fmamk_f32 v41, v76, 0x3e38aa3b, v60
	v_exp_f32_e32 v124, v41
	v_fmamk_f32 v41, v77, 0x3e38aa3b, v60
	v_fmamk_f32 v37, v39, 0x3e38aa3b, v60
	v_fmamk_f32 v34, v34, 0x3e38aa3b, v53
	v_fmamk_f32 v35, v35, 0x3e38aa3b, v53
	v_fmamk_f32 v44, v44, 0x3e38aa3b, v53
	v_fmamk_f32 v45, v45, 0x3e38aa3b, v53
	v_fmamk_f32 v46, v46, 0x3e38aa3b, v53
	v_fmamk_f32 v47, v47, 0x3e38aa3b, v53
	v_fmac_f32_e32 v53, 0x3e38aa3b, v51
	v_exp_f32_e32 v125, v41
	v_exp_f32_e32 v129, v37
	v_mul_f32_e32 v36, 0, v36
	v_exp_f32_e32 v147, v34
	v_exp_f32_e32 v148, v35
	v_exp_f32_e32 v149, v44
	v_exp_f32_e32 v150, v45
	v_exp_f32_e32 v151, v46
	v_exp_f32_e32 v152, v47
	v_exp_f32_e32 v160, v53
	v_fmamk_f32 v28, v28, 0x3e38aa3b, v60
	v_cndmask_b32_e64 v80, v36, 0, vcc
	ds_read_b64_tr_b16 v[38:39], v119 offset:20736
	ds_read_b64_tr_b16 v[36:37], v119 offset:18432
	ds_read_b64_tr_b16 v[44:45], v119 offset:18464
	ds_read_b64_tr_b16 v[48:49], v119 offset:18496
	ds_read_b64_tr_b16 v[52:53], v119 offset:18528
	ds_read_b64_tr_b16 v[46:47], v119 offset:20768
	ds_read_b64_tr_b16 v[50:51], v119 offset:20800
	ds_read_b64_tr_b16 v[54:55], v119 offset:20832
	v_fmamk_f32 v24, v24, 0x3e38aa3b, v60
	v_exp_f32_e32 v130, v28
	v_fmamk_f32 v28, v29, 0x3e38aa3b, v60
	v_exp_f32_e32 v134, v24
	v_fmamk_f32 v24, v25, 0x3e38aa3b, v60
	v_exp_f32_e32 v131, v28
	v_fmamk_f32 v28, v30, 0x3e38aa3b, v60
	v_fmamk_f32 v61, v31, 0x3e38aa3b, v60
	v_exp_f32_e32 v135, v24
	v_fmamk_f32 v24, v26, 0x3e38aa3b, v60
	v_fmac_f32_e32 v60, 0x3e38aa3b, v27
	v_mov_b32_e32 v81, v80
	v_mov_b32_e32 v82, v80
	v_mov_b32_e32 v83, v80
	v_cvt_pk_bf16_f32 v40, v121, v123
	v_cvt_pk_bf16_f32 v41, v124, v125
	v_cvt_pk_bf16_f32 v42, v126, v127
	v_cvt_pk_bf16_f32 v43, v128, v129
	v_exp_f32_e32 v132, v28
	v_exp_f32_e32 v133, v61
	v_exp_f32_e32 v136, v24
	v_exp_f32_e32 v137, v60
	v_mov_b32_e32 v69, v68
	v_mov_b32_e32 v70, v68
	v_mov_b32_e32 v71, v68
	v_cvt_pk_bf16_f32 v32, v122, v146
	v_cvt_pk_bf16_f32 v33, v147, v148
	v_cvt_pk_bf16_f32 v34, v149, v150
	v_cvt_pk_bf16_f32 v35, v151, v152
	s_waitcnt lgkmcnt(2)
	v_mfma_f32_16x16x32_bf16 v[28:31], v[44:47], v[40:43], v[80:83]
	v_cvt_pk_bf16_f32 v88, v130, v131
	v_cvt_pk_bf16_f32 v89, v132, v133
	v_cvt_pk_bf16_f32 v90, v134, v135
	v_mfma_f32_16x16x32_bf16 v[56:59], v[36:39], v[32:35], v[68:71]
	v_cvt_pk_bf16_f32 v91, v136, v137
	v_cvt_pk_bf16_f32 v84, v153, v154
	v_cvt_pk_bf16_f32 v85, v155, v156
	v_mfma_f32_16x16x32_bf16 v[36:39], v[36:39], v[40:43], v[80:83]
	v_cvt_pk_bf16_f32 v86, v157, v158
	v_cvt_pk_bf16_f32 v87, v159, v160
	v_mfma_f32_16x16x32_bf16 v[72:75], v[44:47], v[32:35], v[68:71]
	s_waitcnt lgkmcnt(1)
	v_mfma_f32_16x16x32_bf16 v[44:47], v[48:51], v[32:35], v[68:71]
	v_mfma_f32_16x16x32_bf16 v[76:79], v[48:51], v[40:43], v[80:83]
	s_waitcnt lgkmcnt(0)
	v_mfma_f32_16x16x32_bf16 v[24:27], v[52:55], v[32:35], v[68:71]
	ds_read_b64_tr_b16 v[32:33], v119 offset:23040
	ds_read_b64_tr_b16 v[34:35], v119 offset:25344
	s_nop 0
	v_add_f32_e32 v69, 0, v122
	v_mfma_f32_16x16x32_bf16 v[92:95], v[52:55], v[40:43], v[80:83]
	ds_read_b64_tr_b16 v[40:41], v119 offset:23072
	ds_read_b64_tr_b16 v[138:139], v119 offset:23104
	ds_read_b64_tr_b16 v[142:143], v119 offset:23136
	ds_read_b64_tr_b16 v[42:43], v119 offset:25376
	ds_read_b64_tr_b16 v[140:141], v119 offset:25408
	ds_read_b64_tr_b16 v[144:145], v119 offset:25440
	v_add_f32_e32 v69, v146, v69
	v_add_f32_e32 v69, v147, v69
	s_waitcnt lgkmcnt(2)
	v_mfma_f32_16x16x32_bf16 v[48:51], v[40:43], v[88:91], v[28:31]
	v_add_f32_e32 v69, v148, v69
	v_add_f32_e32 v69, v149, v69
	v_add_f32_e32 v69, v150, v69
	v_lshl_add_u64 v[28:29], v[64:65], 0, v[104:105]
	v_lshlrev_b64 v[28:29], 1, v[28:29]
	v_mfma_f32_16x16x32_bf16 v[60:63], v[32:35], v[88:91], v[36:39]
	v_lshl_add_u64 v[30:31], s[8:9], 0, v[28:29]
	v_lshl_add_u64 v[64:65], v[64:65], 0, v[106:107]
	v_lshlrev_b64 v[64:65], 1, v[64:65]
	s_waitcnt lgkmcnt(0)
	v_mfma_f32_16x16x32_bf16 v[36:39], v[142:145], v[84:87], v[24:27]
	v_add_f32_e32 v69, v151, v69
	v_add_f32_e32 v69, v152, v69
	v_add_f32_e32 v69, v153, v69
	v_lshl_add_u64 v[24:25], s[0:1], 0, v[28:29]
	global_load_dwordx4 v[24:27], v[24:25], off
	s_nop 0
	global_load_dwordx4 v[28:31], v[30:31], off
	s_waitcnt vmcnt(3)
	ds_write_b128 v101, v[16:19] offset:9216
	s_waitcnt vmcnt(2)
	ds_write_b128 v101, v[20:23] offset:27648
	s_waitcnt lgkmcnt(0)
	s_barrier
	ds_read_b128 v[16:19], v118 offset:9216
	ds_read_b128 v[20:23], v118 offset:9280
	v_mfma_f32_16x16x32_bf16 v[52:55], v[40:43], v[84:87], v[72:75]
	v_add_f32_e32 v69, v154, v69
	v_add_f32_e32 v69, v155, v69
	v_add_f32_e32 v69, v156, v69
	s_waitcnt lgkmcnt(1)
	v_mfma_f32_16x16x32_bf16 v[70:73], v[16:19], v[12:15], 0
	v_add_f32_e32 v69, v157, v69
	v_add_f32_e32 v69, v158, v69
	v_add_f32_e32 v69, v159, v69
	v_mfma_f32_16x16x32_bf16 v[16:19], v[16:19], v[8:11], 0
	v_add_f32_e32 v69, v160, v69
	v_add_f32_e32 v122, v69, v68
	v_mfma_f32_16x16x32_bf16 v[56:59], v[32:35], v[84:87], v[56:59]
	v_mfma_f32_16x16x32_bf16 v[44:47], v[138:141], v[84:87], v[44:47]
	v_mfma_f32_16x16x32_bf16 v[40:43], v[138:141], v[88:91], v[76:79]
	v_mfma_f32_16x16x32_bf16 v[32:35], v[142:145], v[88:91], v[92:95]
	s_waitcnt lgkmcnt(0)
	v_mfma_f32_16x16x32_bf16 v[86:89], v[20:23], v[4:7], v[70:73]
	v_mfma_f32_16x16x32_bf16 v[72:75], v[20:23], v[0:3], v[16:19]
	s_nop 2
	ds_read_b128 v[16:19], v118 offset:11520
	ds_read_b128 v[20:23], v118 offset:11584
	ds_read_b128 v[90:93], v118 offset:13824
	s_nop 0
	v_max_f32_e32 v81, v89, v89
	s_waitcnt lgkmcnt(2)
	v_mfma_f32_16x16x32_bf16 v[76:79], v[16:19], v[12:15], 0
	v_mfma_f32_16x16x32_bf16 v[16:19], v[16:19], v[8:11], 0
	s_waitcnt lgkmcnt(1)
	v_mfma_f32_16x16x32_bf16 v[82:85], v[20:23], v[4:7], v[76:79]
	v_mfma_f32_16x16x32_bf16 v[76:79], v[20:23], v[0:3], v[16:19]
	v_lshl_add_u64 v[20:21], s[8:9], 0, v[64:65]
	s_nop 3
	v_lshl_add_u64 v[16:17], s[0:1], 0, v[64:65]
	ds_read_b128 v[64:67], v118 offset:13888
	global_load_dwordx4 v[16:19], v[16:17], off
	s_nop 0
	global_load_dwordx4 v[20:23], v[20:21], off
	s_waitcnt lgkmcnt(1)
	v_mfma_f32_16x16x32_bf16 v[94:97], v[90:93], v[12:15], 0
	ds_read_b128 v[142:145], v118 offset:16128
	v_mfma_f32_16x16x32_bf16 v[138:141], v[90:93], v[8:11], 0
	s_waitcnt lgkmcnt(1)
	v_mfma_f32_16x16x32_bf16 v[90:93], v[64:67], v[4:7], v[94:97]
	v_mfma_f32_16x16x32_bf16 v[64:67], v[64:67], v[0:3], v[138:141]
	s_nop 4
	ds_read_b128 v[138:141], v118 offset:16192
	s_waitcnt lgkmcnt(1)
	v_mfma_f32_16x16x32_bf16 v[94:97], v[142:145], v[12:15], 0
	v_mfma_f32_16x16x32_bf16 v[142:145], v[142:145], v[8:11], 0
	s_waitcnt lgkmcnt(0)
	v_mfma_f32_16x16x32_bf16 v[94:97], v[138:141], v[4:7], v[94:97]
	v_mfma_f32_16x16x32_bf16 v[68:71], v[138:141], v[0:3], v[142:145]
	v_max_f32_e32 v138, v88, v88
	v_max_f32_e32 v81, v138, v81
	v_max_f32_e32 v138, v85, v85
	v_max_f32_e32 v139, v84, v84
	v_max_f32_e32 v138, v139, v138
	v_max3_f32 v81, v86, v87, v81
	v_max3_f32 v138, v82, v83, v138
	v_max3_f32 v81, v81, s17, v138
	v_max_f32_e32 v138, v93, v93
	v_max_f32_e32 v139, v92, v92
	v_max_f32_e32 v138, v139, v138
	v_max_f32_e32 v139, v97, v97
	v_max_f32_e32 v140, v96, v96
	v_max_f32_e32 v139, v140, v139
	v_max3_f32 v138, v90, v91, v138
	v_max3_f32 v139, v94, v95, v139
	v_max3_f32 v81, v81, v138, v139
	v_mov_b32_e32 v138, v81
	s_nop 1
	v_permlane16_swap_b32_e32 v81, v138
	v_max_f32_e32 v138, v138, v138
	v_max_f32_e32 v81, v81, v81
	v_max_f32_e32 v81, v81, v138
	v_mov_b32_e32 v138, v81
	s_nop 1
	v_permlane32_swap_b32_e32 v81, v138
	v_max_f32_e32 v138, v138, v138
	v_max_f32_e32 v81, v81, v81
	v_max_f32_e32 v81, v81, v138
	v_fma_f32 v81, v81, s18, 0
	v_sub_f32_e32 v138, v81, v113
	v_cmp_ge_f32_e32 vcc, s19, v138
	s_cmp_eq_u64 vcc, exec
	s_cselect_b64 s[0:1], -1, 0
	v_max_f32_e32 v81, v113, v81
	s_mov_b64 vcc, s[0:1]
	s_cbranch_vccnz .LBB0_314
	v_sub_f32_e32 v138, v113, v81
	v_exp_f32_e32 v138, v138
	s_nop 0
	v_mul_f32_e32 v122, v122, v138
	v_pk_mul_f32 v[58:59], v[58:59], v[138:139] op_sel_hi:[1,0]
	v_pk_mul_f32 v[56:57], v[56:57], v[138:139] op_sel_hi:[1,0]
	v_pk_mul_f32 v[54:55], v[54:55], v[138:139] op_sel_hi:[1,0]
	v_pk_mul_f32 v[52:53], v[52:53], v[138:139] op_sel_hi:[1,0]
	v_pk_mul_f32 v[46:47], v[46:47], v[138:139] op_sel_hi:[1,0]
	v_pk_mul_f32 v[44:45], v[44:45], v[138:139] op_sel_hi:[1,0]
	v_pk_mul_f32 v[38:39], v[38:39], v[138:139] op_sel_hi:[1,0]
	v_pk_mul_f32 v[36:37], v[36:37], v[138:139] op_sel_hi:[1,0]

.LBB0_1083:
	s_ashr_i32 s20, s13, 6
	s_ashr_i32 s21, s20, 31
	s_lshl_b64 s[0:1], s[20:21], 12
	s_and_b32 s2, s12, 0xf00
	s_add_u32 s2, s2, s8
	s_addc_u32 s3, 0, s9
	s_add_u32 s0, s2, s0
	s_addc_u32 s1, s3, s1
	s_mul_i32 s2, s1, 0x1400
	s_mul_hi_u32 s3, s0, 0x1400
	s_add_i32 s3, s3, s2
	s_mul_i32 s2, s0, 0x1400
	s_add_u32 s4, s60, s2
	s_addc_u32 s3, s61, s3
	s_and_b32 s2, s12, 0xc0
	s_lshl_b32 s2, s2, 1
	s_add_u32 s22, s4, s2
	s_addc_u32 s23, s3, 0
	s_add_u32 s4, s11, s2
	s_addc_u32 s5, s14, 0
	s_add_u32 s6, s19, s2
	s_addc_u32 s7, s24, 0
	s_lshl_b64 s[20:21], s[20:21], 18
	v_lshl_add_u64 v[32:33], s[20:21], 0, v[104:105]
	v_lshl_add_u64 v[0:1], s[22:23], 0, v[152:153]
	v_mov_b32_e32 v107, v153
	v_or_b32_e32 v16, v32, v112
	v_mov_b32_e32 v17, v33
	v_lshl_add_u64 v[0:1], v[0:1], 0, v[106:107]
	s_mov_b64 s[22:23], 0x14000
	v_lshlrev_b64 v[20:21], 1, v[16:17]
	s_barrier
	global_load_dwordx4 v[8:11], v[0:1], off offset:1536
	global_load_dwordx4 v[4:7], v[0:1], off offset:1600
	v_lshl_add_u64 v[0:1], v[0:1], 0, s[22:23]
	v_lshl_add_u64 v[16:17], s[4:5], 0, v[20:21]
	global_load_dwordx4 v[12:15], v[0:1], off offset:1536
	s_nop 0
	global_load_dwordx4 v[0:3], v[0:1], off offset:1600
	v_lshl_add_u64 v[20:21], s[6:7], 0, v[20:21]
	global_load_dwordx4 v[16:19], v[16:17], off
	v_lshl_add_u64 v[24:25], v[32:33], 0, v[98:99]
	global_load_dwordx4 v[20:23], v[20:21], off
	v_lshlrev_b64 v[28:29], 1, v[24:25]
	v_lshl_add_u64 v[24:25], s[4:5], 0, v[28:29]
	v_lshl_add_u64 v[28:29], s[6:7], 0, v[28:29]
	global_load_dwordx4 v[24:27], v[24:25], off
	v_lshl_add_u64 v[34:35], v[32:33], 0, v[102:103]
	global_load_dwordx4 v[28:31], v[28:29], off
	v_lshlrev_b64 v[34:35], 1, v[34:35]
	v_lshl_add_u64 v[72:73], s[4:5], 0, v[34:35]
	v_lshl_add_u64 v[74:75], s[6:7], 0, v[34:35]
	s_waitcnt vmcnt(3)
	ds_write_b128 v121, v[16:19]
	s_waitcnt vmcnt(2)
	ds_write_b128 v121, v[20:23] offset:18432
	v_lshl_add_u64 v[16:17], v[32:33], 0, v[100:101]
	v_lshlrev_b64 v[16:17], 1, v[16:17]
	v_lshl_add_u64 v[20:21], s[6:7], 0, v[16:17]
	v_lshl_add_u64 v[16:17], s[4:5], 0, v[16:17]
	s_waitcnt lgkmcnt(0)
	s_barrier
	global_load_dwordx4 v[16:19], v[16:17], off
	s_nop 0
	global_load_dwordx4 v[20:23], v[20:21], off
	ds_read_b128 v[32:35], v113
	ds_read_b128 v[40:43], v113 offset:64
	s_waitcnt lgkmcnt(1)
	v_mfma_f32_16x16x32_bf16 v[36:39], v[32:35], v[8:11], 0
	ds_read_b128 v[44:47], v113 offset:2368
	ds_read_b128 v[48:51], v113 offset:4672
	ds_read_b128 v[64:67], v113 offset:6976
	s_waitcnt lgkmcnt(3)
	v_mfma_f32_16x16x32_bf16 v[60:63], v[40:43], v[4:7], v[36:39]
	s_nop 2
	ds_read_b128 v[36:39], v113 offset:2304
	v_mfma_f32_16x16x32_bf16 v[32:35], v[32:35], v[12:15], 0
	v_mfma_f32_16x16x32_bf16 v[32:35], v[40:43], v[0:3], v[32:35]
	s_waitcnt lgkmcnt(0)
	v_mfma_f32_16x16x32_bf16 v[40:43], v[36:39], v[8:11], 0
	v_mfma_f32_16x16x32_bf16 v[56:59], v[44:47], v[4:7], v[40:43]
	v_mfma_f32_16x16x32_bf16 v[36:39], v[36:39], v[12:15], 0
	s_nop 5
	ds_read_b128 v[40:43], v113 offset:4608
	v_mfma_f32_16x16x32_bf16 v[36:39], v[44:47], v[0:3], v[36:39]
	s_waitcnt lgkmcnt(0)
	v_mfma_f32_16x16x32_bf16 v[44:47], v[40:43], v[8:11], 0
	v_mfma_f32_16x16x32_bf16 v[52:55], v[48:51], v[4:7], v[44:47]
	s_nop 6
	ds_read_b128 v[44:47], v113 offset:6912
	v_mfma_f32_16x16x32_bf16 v[40:43], v[40:43], v[12:15], 0
	v_mfma_f32_16x16x32_bf16 v[40:43], v[48:51], v[0:3], v[40:43]
	s_waitcnt lgkmcnt(0)
	v_mfma_f32_16x16x32_bf16 v[48:51], v[44:47], v[8:11], 0
	v_mfma_f32_16x16x32_bf16 v[44:47], v[44:47], v[12:15], 0
	v_mfma_f32_16x16x32_bf16 v[48:51], v[64:67], v[4:7], v[48:51]
	v_mfma_f32_16x16x32_bf16 v[44:47], v[64:67], v[0:3], v[44:47]
	v_max_f32_e32 v64, v63, v63
	v_max_f32_e32 v65, v62, v62
	v_max_f32_e32 v64, v65, v64
	v_max_f32_e32 v65, v59, v59
	v_max_f32_e32 v66, v58, v58
	v_max_f32_e32 v65, v66, v65
	v_max3_f32 v64, v60, v61, v64
	v_max3_f32 v65, v56, v57, v65
	v_max3_f32 v64, v64, s95, v65
	v_max_f32_e32 v65, v55, v55
	v_max_f32_e32 v66, v54, v54
	v_max_f32_e32 v65, v66, v65
	v_max_f32_e32 v66, v51, v51
	v_max_f32_e32 v67, v50, v50
	v_max_f32_e32 v66, v67, v66
	v_max3_f32 v65, v52, v53, v65
	v_max3_f32 v66, v48, v49, v66
	v_max3_f32 v64, v64, v65, v66
	v_mov_b32_e32 v65, v64
	s_nop 1
	v_permlane16_swap_b32_e32 v64, v65
	v_max_f32_e32 v65, v65, v65
	v_max_f32_e32 v64, v64, v64
	v_max_f32_e32 v64, v64, v65
	v_mov_b32_e32 v65, v64
	s_nop 1
	v_permlane32_swap_b32_e32 v64, v65
	v_max_f32_e32 v65, v65, v65
	v_max_f32_e32 v64, v64, v64
	v_max_f32_e32 v64, v64, v65
	v_fma_f32 v64, v64, s96, 0
	v_add_f32_e32 v65, 0x7149f2ca, v64
	v_cmp_ge_f32_e32 vcc, s97, v65
	s_cmp_eq_u64 vcc, exec
	s_cselect_b64 vcc, -1, 0
	v_max_f32_e32 v64, 0xf149f2ca, v64
	v_cndmask_b32_e32 v107, v64, v192, vcc
	v_sub_f32_e32 v65, 0, v107
	v_fmamk_f32 v60, v60, 0x3e38aa3b, v65
	v_exp_f32_e32 v60, v60
	v_fmamk_f32 v61, v61, 0x3e38aa3b, v65
	v_exp_f32_e32 v61, v61
	v_fmamk_f32 v62, v62, 0x3e38aa3b, v65
	v_exp_f32_e32 v62, v62
	v_fmamk_f32 v63, v63, 0x3e38aa3b, v65
	v_exp_f32_e32 v63, v63
	v_fmamk_f32 v56, v56, 0x3e38aa3b, v65
	v_add_f32_e32 v66, 0, v60
	v_exp_f32_e32 v67, v56
	v_add_f32_e32 v66, v61, v66
	v_add_f32_e32 v66, v62, v66
	v_add_f32_e32 v66, v63, v66
	v_fmamk_f32 v57, v57, 0x3e38aa3b, v65
	v_add_f32_e32 v56, v67, v66
	v_exp_f32_e32 v66, v57
	v_fmamk_f32 v57, v58, 0x3e38aa3b, v65
	v_exp_f32_e32 v68, v57
	v_fmamk_f32 v57, v59, 0x3e38aa3b, v65
	v_exp_f32_e32 v59, v57
	v_fmamk_f32 v52, v52, 0x3e38aa3b, v65
	v_exp_f32_e32 v52, v52
	v_fmamk_f32 v53, v53, 0x3e38aa3b, v65
	v_add_f32_e32 v56, v66, v56
	v_exp_f32_e32 v53, v53
	v_fmamk_f32 v54, v54, 0x3e38aa3b, v65
	v_add_f32_e32 v56, v68, v56
	v_exp_f32_e32 v54, v54
	v_fmamk_f32 v55, v55, 0x3e38aa3b, v65
	v_add_f32_e32 v56, v59, v56
	v_exp_f32_e32 v55, v55
	v_fmamk_f32 v48, v48, 0x3e38aa3b, v65
	v_add_f32_e32 v56, v52, v56
	v_exp_f32_e32 v69, v48
	v_fmamk_f32 v49, v49, 0x3e38aa3b, v65
	v_add_f32_e32 v56, v53, v56
	v_exp_f32_e32 v70, v49
	v_fmamk_f32 v49, v50, 0x3e38aa3b, v65
	v_add_f32_e32 v56, v54, v56
	v_exp_f32_e32 v71, v49
	v_fmac_f32_e32 v65, 0x3e38aa3b, v51
	v_add_f32_e32 v56, v55, v56
	v_exp_f32_e32 v65, v65
	v_add_f32_e32 v48, v69, v56
	v_add_f32_e32 v48, v70, v48
	v_add_f32_e32 v48, v71, v48
	v_add_f32_e32 v56, v65, v48
	v_sub_f32_e32 v48, 0xf149f2ca, v64
	v_exp_f32_e32 v48, v48
	v_cvt_pk_bf16_f32 v57, v62, v63
	v_max_f32_e32 v62, v38, v38
	v_max_f32_e32 v63, v46, v46
	v_mul_f32_e32 v48, 0, v48
	v_cndmask_b32_e64 v48, v48, 0, vcc
	v_add_f32_e32 v109, v56, v48
	v_cvt_pk_bf16_f32 v56, v60, v61
	v_max_f32_e32 v60, v35, v35
	v_max_f32_e32 v61, v34, v34
	v_max_f32_e32 v60, v61, v60
	v_max_f32_e32 v61, v39, v39
	v_max_f32_e32 v61, v62, v61
	v_max3_f32 v60, v32, v33, v60
	v_max3_f32 v61, v36, v37, v61
	v_max3_f32 v60, v60, s95, v61
	v_max_f32_e32 v61, v43, v43
	v_max_f32_e32 v62, v42, v42
	v_max_f32_e32 v61, v62, v61
	v_max_f32_e32 v62, v47, v47
	v_max_f32_e32 v62, v63, v62
	v_max3_f32 v61, v40, v41, v61
	v_max3_f32 v62, v44, v45, v62
	v_max3_f32 v60, v60, v61, v62
	v_mov_b32_e32 v61, v60
	s_nop 1
	v_permlane16_swap_b32_e32 v60, v61
	v_max_f32_e32 v61, v61, v61
	v_max_f32_e32 v60, v60, v60
	v_max_f32_e32 v60, v60, v61
	v_mov_b32_e32 v61, v60
	s_nop 1
	v_permlane32_swap_b32_e32 v60, v61
	v_max_f32_e32 v61, v61, v61
	v_max_f32_e32 v60, v60, v60
	v_max_f32_e32 v60, v60, v61
	v_fma_f32 v60, v60, s96, 0
	v_add_f32_e32 v61, 0x7149f2ca, v60
	v_cmp_ge_f32_e32 vcc, s97, v61
	s_cmp_eq_u64 vcc, exec
	s_cselect_b64 vcc, -1, 0
	v_max_f32_e32 v60, 0xf149f2ca, v60
	v_cndmask_b32_e32 v111, v60, v192, vcc
	v_sub_f32_e32 v61, 0, v111
	v_fmamk_f32 v32, v32, 0x3e38aa3b, v61
	v_exp_f32_e32 v115, v32
	v_fmamk_f32 v32, v33, 0x3e38aa3b, v61
	v_exp_f32_e32 v117, v32
	v_fmamk_f32 v32, v34, 0x3e38aa3b, v61
	v_exp_f32_e32 v118, v32
	v_fmamk_f32 v32, v35, 0x3e38aa3b, v61
	v_exp_f32_e32 v120, v32
	v_fmamk_f32 v32, v36, 0x3e38aa3b, v61
	v_exp_f32_e32 v122, v32
	v_fmamk_f32 v32, v37, 0x3e38aa3b, v61
	v_exp_f32_e32 v123, v32
	v_fmamk_f32 v32, v38, 0x3e38aa3b, v61
	v_exp_f32_e32 v124, v32
	v_fmamk_f32 v32, v39, 0x3e38aa3b, v61
	v_exp_f32_e32 v125, v32
	v_fmamk_f32 v32, v40, 0x3e38aa3b, v61
	v_exp_f32_e32 v126, v32
	v_fmamk_f32 v32, v41, 0x3e38aa3b, v61
	v_exp_f32_e32 v127, v32
	v_fmamk_f32 v32, v42, 0x3e38aa3b, v61
	v_exp_f32_e32 v128, v32
	v_fmamk_f32 v32, v43, 0x3e38aa3b, v61
	v_exp_f32_e32 v129, v32
	v_fmamk_f32 v32, v44, 0x3e38aa3b, v61
	v_exp_f32_e32 v130, v32
	v_fmamk_f32 v32, v45, 0x3e38aa3b, v61
	v_exp_f32_e32 v131, v32
	v_fmamk_f32 v32, v46, 0x3e38aa3b, v61
	v_exp_f32_e32 v132, v32
	v_sub_f32_e32 v32, 0xf149f2ca, v60
	v_exp_f32_e32 v32, v32
	ds_read_b64_tr_b16 v[38:39], v119 offset:20736
	ds_read_b64_tr_b16 v[36:37], v119 offset:18432
	ds_read_b64_tr_b16 v[40:41], v119 offset:18464
	v_mov_b32_e32 v49, v48
	v_mov_b32_e32 v50, v48
	v_mul_f32_e32 v32, 0, v32
	v_cndmask_b32_e64 v64, v32, 0, vcc
	v_mov_b32_e32 v51, v48
	v_cvt_pk_bf16_f32 v58, v67, v66
	v_cvt_pk_bf16_f32 v59, v68, v59
	v_cvt_pk_bf16_f32 v52, v52, v53
	v_cvt_pk_bf16_f32 v53, v54, v55
	v_cvt_pk_bf16_f32 v55, v71, v65
	v_fmac_f32_e32 v61, 0x3e38aa3b, v47
	v_mov_b32_e32 v65, v64
	v_mov_b32_e32 v66, v64
	v_mov_b32_e32 v67, v64
	v_cvt_pk_bf16_f32 v32, v115, v117
	v_cvt_pk_bf16_f32 v33, v118, v120
	v_cvt_pk_bf16_f32 v34, v122, v123
	v_cvt_pk_bf16_f32 v35, v124, v125
	v_exp_f32_e32 v133, v61
	s_waitcnt lgkmcnt(1)
	v_mfma_f32_16x16x32_bf16 v[44:47], v[36:39], v[56:59], v[48:51]
	ds_read_b64_tr_b16 v[42:43], v119 offset:20768
	v_cvt_pk_bf16_f32 v54, v69, v70
	v_cvt_pk_bf16_f32 v68, v126, v127
	v_mfma_f32_16x16x32_bf16 v[60:63], v[36:39], v[32:35], v[64:67]
	ds_read_b64_tr_b16 v[36:37], v119 offset:18496
	ds_read_b64_tr_b16 v[38:39], v119 offset:20800
	v_cvt_pk_bf16_f32 v69, v128, v129
	v_cvt_pk_bf16_f32 v70, v130, v131
	s_waitcnt lgkmcnt(0)
	v_mfma_f32_16x16x32_bf16 v[84:87], v[36:39], v[56:59], v[48:51]
	v_cvt_pk_bf16_f32 v71, v132, v133
	v_mfma_f32_16x16x32_bf16 v[88:91], v[36:39], v[32:35], v[64:67]
	ds_read_b64_tr_b16 v[36:37], v119 offset:18528
	ds_read_b64_tr_b16 v[38:39], v119 offset:20832
	v_mfma_f32_16x16x32_bf16 v[80:83], v[40:43], v[32:35], v[64:67]
	s_waitcnt lgkmcnt(0)
	v_mfma_f32_16x16x32_bf16 v[134:137], v[36:39], v[32:35], v[64:67]
	ds_read_b64_tr_b16 v[32:33], v119 offset:23040
	ds_read_b64_tr_b16 v[34:35], v119 offset:25344
	v_mfma_f32_16x16x32_bf16 v[76:79], v[40:43], v[56:59], v[48:51]
	v_mfma_f32_16x16x32_bf16 v[92:95], v[36:39], v[56:59], v[48:51]
	s_waitcnt lgkmcnt(0)
	v_mfma_f32_16x16x32_bf16 v[36:39], v[32:35], v[52:55], v[44:47]
	v_mfma_f32_16x16x32_bf16 v[40:43], v[32:35], v[68:71], v[60:63]
	ds_read_b64_tr_b16 v[32:33], v119 offset:23072
	ds_read_b64_tr_b16 v[34:35], v119 offset:25376
	s_waitcnt lgkmcnt(0)
	v_mfma_f32_16x16x32_bf16 v[56:59], v[32:35], v[52:55], v[76:79]
	v_mfma_f32_16x16x32_bf16 v[60:63], v[32:35], v[68:71], v[80:83]
	ds_read_b64_tr_b16 v[32:33], v119 offset:23104
	ds_read_b64_tr_b16 v[34:35], v119 offset:25408
	ds_read_b64_tr_b16 v[76:77], v119 offset:23136
	ds_read_b64_tr_b16 v[78:79], v119 offset:25440
	s_waitcnt vmcnt(3)
	ds_write_b128 v121, v[24:27] offset:9216
	s_waitcnt vmcnt(2)
	ds_write_b128 v121, v[28:31] offset:27648
	s_waitcnt lgkmcnt(0)
	s_barrier
	global_load_dwordx4 v[24:27], v[72:73], off
	global_load_dwordx4 v[28:31], v[74:75], off
	v_mfma_f32_16x16x32_bf16 v[44:47], v[32:35], v[52:55], v[84:87]
	v_mfma_f32_16x16x32_bf16 v[48:51], v[32:35], v[68:71], v[88:91]
	v_mfma_f32_16x16x32_bf16 v[32:35], v[76:79], v[52:55], v[92:95]
	s_nop 1
	ds_read_b128 v[86:89], v113 offset:11584
	v_mfma_f32_16x16x32_bf16 v[52:55], v[76:79], v[68:71], v[134:137]
	ds_read_b128 v[66:69], v113 offset:9216
	ds_read_b128 v[74:77], v113 offset:9280
	ds_read_b128 v[90:93], v113 offset:13888
	s_waitcnt lgkmcnt(2)
	v_mfma_f32_16x16x32_bf16 v[70:73], v[66:69], v[8:11], 0
	ds_read_b128 v[134:137], v113 offset:16192
	s_waitcnt lgkmcnt(2)
	v_mfma_f32_16x16x32_bf16 v[82:85], v[74:77], v[4:7], v[70:73]
	s_nop 4
	ds_read_b128 v[70:73], v113 offset:11520
	v_mfma_f32_16x16x32_bf16 v[66:69], v[66:69], v[12:15], 0
	s_nop 0
	v_max_f32_e32 v65, v85, v85
	v_mfma_f32_16x16x32_bf16 v[66:69], v[74:77], v[0:3], v[66:69]
	s_waitcnt lgkmcnt(0)
	v_mfma_f32_16x16x32_bf16 v[74:77], v[70:73], v[8:11], 0
	v_mfma_f32_16x16x32_bf16 v[78:81], v[86:89], v[4:7], v[74:77]
	v_mfma_f32_16x16x32_bf16 v[70:73], v[70:73], v[12:15], 0
	s_nop 5
	ds_read_b128 v[74:77], v113 offset:13824
	v_mfma_f32_16x16x32_bf16 v[70:73], v[86:89], v[0:3], v[70:73]
	s_waitcnt lgkmcnt(0)
	v_mfma_f32_16x16x32_bf16 v[86:89], v[74:77], v[8:11], 0
	v_mfma_f32_16x16x32_bf16 v[74:77], v[74:77], v[12:15], 0
	v_mfma_f32_16x16x32_bf16 v[86:89], v[90:93], v[4:7], v[86:89]
	v_mfma_f32_16x16x32_bf16 v[74:77], v[90:93], v[0:3], v[74:77]
	ds_read_b128 v[90:93], v113 offset:16128
	s_waitcnt lgkmcnt(0)
	v_mfma_f32_16x16x32_bf16 v[94:97], v[90:93], v[8:11], 0
	v_mfma_f32_16x16x32_bf16 v[90:93], v[90:93], v[12:15], 0
	v_mfma_f32_16x16x32_bf16 v[94:97], v[134:137], v[4:7], v[94:97]
	v_mfma_f32_16x16x32_bf16 v[90:93], v[134:137], v[0:3], v[90:93]
	v_max_f32_e32 v134, v84, v84
	v_max_f32_e32 v65, v134, v65
	v_max_f32_e32 v134, v81, v81
	v_max_f32_e32 v135, v80, v80
	v_max_f32_e32 v134, v135, v134
	v_max3_f32 v65, v82, v83, v65
	v_max3_f32 v134, v78, v79, v134
	v_max3_f32 v65, v65, s95, v134
	v_max_f32_e32 v134, v89, v89
	v_max_f32_e32 v135, v88, v88
	v_max_f32_e32 v134, v135, v134
	v_max_f32_e32 v135, v97, v97
	v_max_f32_e32 v136, v96, v96
	v_max_f32_e32 v135, v136, v135
	v_max3_f32 v134, v86, v87, v134
	v_max3_f32 v135, v94, v95, v135
	v_max3_f32 v65, v65, v134, v135
	v_mov_b32_e32 v134, v65
	s_nop 1
	v_permlane16_swap_b32_e32 v65, v134
	v_max_f32_e32 v134, v134, v134
	v_max_f32_e32 v65, v65, v65
	v_max_f32_e32 v65, v65, v134
	v_mov_b32_e32 v134, v65
	s_nop 1
	v_permlane32_swap_b32_e32 v65, v134
	v_max_f32_e32 v134, v134, v134
	v_max_f32_e32 v65, v65, v65
	v_max_f32_e32 v65, v65, v134
	v_fma_f32 v65, v65, s96, 0
	v_sub_f32_e32 v134, v65, v107
	v_cmp_ge_f32_e32 vcc, s97, v134
	s_cmp_eq_u64 vcc, exec
	s_cselect_b64 s[36:37], -1, 0
	v_max_f32_e32 v65, v107, v65
	s_mov_b64 vcc, s[36:37]
	s_cbranch_vccnz .LBB0_1085
	v_sub_f32_e32 v134, v107, v65
	v_exp_f32_e32 v134, v134
	s_nop 0
	v_mul_f32_e32 v109, v109, v134
	v_pk_mul_f32 v[38:39], v[38:39], v[134:135] op_sel_hi:[1,0]
	v_pk_mul_f32 v[36:37], v[36:37], v[134:135] op_sel_hi:[1,0]
	v_pk_mul_f32 v[58:59], v[58:59], v[134:135] op_sel_hi:[1,0]
	v_pk_mul_f32 v[56:57], v[56:57], v[134:135] op_sel_hi:[1,0]
	v_pk_mul_f32 v[46:47], v[46:47], v[134:135] op_sel_hi:[1,0]
	v_pk_mul_f32 v[44:45], v[44:45], v[134:135] op_sel_hi:[1,0]
	v_pk_mul_f32 v[34:35], v[34:35], v[134:135] op_sel_hi:[1,0]
	v_pk_mul_f32 v[32:33], v[32:33], v[134:135] op_sel_hi:[1,0]
